# P0 row loop rewritten by hand: packed-f32 FMAs for the dt dot products, transposing permlane/DPP lane reduction for both rows at once, one softplus per row pair, row loads prefetched one row ahead
# speedup vs baseline: 1.0109x; 1.0091x over previous
; __device__ __forceinline__ void p0_prologue(const Args& a, LAS unsigned char* lds, int gw, int NGW, int lane, int wave) {
;     ...
;     float wd[8][16];
;     { const float* Win = a.in[I_WIN]; const float* pw = a.in[I_PREMIX];
; #pragma unroll
;       for (int j = 0; j < 8; ++j)
; #pragma unroll
;           for (int q = 0; q < 4; ++q)
; #pragma unroll
;               for (int e = 0; e < 4; ++e) { const int k = q * 256 + lane * 4 + e; wd[j][q * 4 + e] = Win[(size_t)k * 2056 + 1536 + j] * pw[k]; } }
;     bf16_t* xb = (bf16_t*)(ws + WS_HB); float* rstd1 = (float*)(ws + WS_RSTD1); float* dtv = (float*)(ws + WS_DTV);
;     const float* dtb = a.in[I_DTB];
;     for (int row0 = 2 * gw; row0 < R; row0 += 2 * NGW) {
;         f32x4 vv[2][4];
; #pragma unroll
;         for (int rr = 0; rr < 2; ++rr) { const int row = row0 + rr;
;             const float* xr = row < RP ? a.in[I_XP] + (size_t)row * DM : a.in[I_XS] + (size_t)(row - RP) * DM;
; #pragma unroll
;             for (int q = 0; q < 4; ++q) vv[rr][q] = *(const f32x4*)(xr + q * 256 + lane * 4); }
.LBB0_64:
	s_or_b64 exec, exec, s[2:3]
	v_readlane_b32 s2, v254, 40
	s_cmp_lt_i32 s2, 0x8080
	s_cbranch_scc0 .LBB0_80
	s_load_dwordx4 s[8:11], s[0:1], 0x0
	s_load_dwordx2 s[12:13], s[0:1], 0x38
	s_load_dwordx2 s[14:15], s[0:1], 0x40
	s_load_dwordx2 s[16:17], s[0:1], 0x58
	s_lshl_b32 s38, s38, 4
	v_readlane_b32 s36, v254, 40
	v_lshlrev_b32_e32 v1, 4, v176
	v_mul_u32_u24_e32 v226, 0x8080, v176
	v_add_u32_e32 v226, 0x1800, v226
	v_bfe_u32 v26, v176, 4, 1
	v_bfe_u32 v27, v176, 3, 1
	v_bfe_u32 v28, v176, 2, 1
	v_lshl_or_b32 v26, v27, 1, v26
	v_lshl_or_b32 v26, v28, 2, v26
	v_lshlrev_b32_e32 v26, 2, v26
	v_and_b32_e32 v27, 32, v176
	v_add_u32_e32 v34, v26, v27
	v_lshrrev_b32_e32 v35, 3, v27
	v_lshlrev_b32_e32 v38, 3, v176
	s_lshl_b32 s36, s36, 1
	s_waitcnt lgkmcnt(0)
	s_mov_b64 s[20:21], s[14:15]
	global_load_dwordx4 v[40:43], v226, s[20:21]
	global_load_dwordx4 v[44:47], v226, s[20:21] offset:16
	s_add_u32 s20, s14, 0x2020
	s_addc_u32 s21, s15, 0
	global_load_dwordx4 v[48:51], v226, s[20:21]
	global_load_dwordx4 v[52:55], v226, s[20:21] offset:16
	s_add_u32 s20, s14, 0x4040
	s_addc_u32 s21, s15, 0
	global_load_dwordx4 v[56:59], v226, s[20:21]
	global_load_dwordx4 v[60:63], v226, s[20:21] offset:16
	s_add_u32 s20, s14, 0x6060
	s_addc_u32 s21, s15, 0
	global_load_dwordx4 v[64:67], v226, s[20:21]
	global_load_dwordx4 v[68:71], v226, s[20:21] offset:16
	s_add_u32 s20, s14, 0x202000
	s_addc_u32 s21, s15, 0
	global_load_dwordx4 v[72:75], v226, s[20:21]
	global_load_dwordx4 v[76:79], v226, s[20:21] offset:16
	s_add_u32 s20, s14, 0x204020
	s_addc_u32 s21, s15, 0
	global_load_dwordx4 v[80:83], v226, s[20:21]
	global_load_dwordx4 v[84:87], v226, s[20:21] offset:16
	s_add_u32 s20, s14, 0x206040
	s_addc_u32 s21, s15, 0
	global_load_dwordx4 v[88:91], v226, s[20:21]
	global_load_dwordx4 v[92:95], v226, s[20:21] offset:16
	s_add_u32 s20, s14, 0x208060
	s_addc_u32 s21, s15, 0
	global_load_dwordx4 v[96:99], v226, s[20:21]
	global_load_dwordx4 v[100:103], v226, s[20:21] offset:16
	s_add_u32 s20, s14, 0x404000
	s_addc_u32 s21, s15, 0
	global_load_dwordx4 v[104:107], v226, s[20:21]
	global_load_dwordx4 v[108:111], v226, s[20:21] offset:16
	s_add_u32 s20, s14, 0x406020
	s_addc_u32 s21, s15, 0
	global_load_dwordx4 v[112:115], v226, s[20:21]
	global_load_dwordx4 v[116:119], v226, s[20:21] offset:16
	s_add_u32 s20, s14, 0x408040
	s_addc_u32 s21, s15, 0
	global_load_dwordx4 v[120:123], v226, s[20:21]
	global_load_dwordx4 v[124:127], v226, s[20:21] offset:16
	s_add_u32 s20, s14, 0x40a060
	s_addc_u32 s21, s15, 0
	global_load_dwordx4 v[128:131], v226, s[20:21]
	global_load_dwordx4 v[132:135], v226, s[20:21] offset:16
	s_add_u32 s20, s14, 0x606000
	s_addc_u32 s21, s15, 0
	global_load_dwordx4 v[136:139], v226, s[20:21]
	global_load_dwordx4 v[140:143], v226, s[20:21] offset:16
	s_add_u32 s20, s14, 0x608020
	s_addc_u32 s21, s15, 0
	global_load_dwordx4 v[144:147], v226, s[20:21]
	global_load_dwordx4 v[148:151], v226, s[20:21] offset:16
	s_add_u32 s20, s14, 0x60a040
	s_addc_u32 s21, s15, 0
	global_load_dwordx4 v[152:155], v226, s[20:21]
	global_load_dwordx4 v[156:159], v226, s[20:21] offset:16
	s_add_u32 s20, s14, 0x60c060
	s_addc_u32 s21, s15, 0
	global_load_dwordx4 v[160:163], v226, s[20:21]
	global_load_dwordx4 v[164:167], v226, s[20:21] offset:16
	global_load_dwordx4 v[196:199], v1, s[12:13]
	global_load_dwordx4 v[200:203], v1, s[12:13] offset:1024
	global_load_dwordx4 v[204:207], v1, s[12:13] offset:2048
	global_load_dwordx4 v[208:211], v1, s[12:13] offset:3072
	global_load_dword v18, v26, s[16:17]
	s_mov_b32 s18, 0xf800000
	s_mov_b32 s19, 0x41a00000
	s_mov_b32 s23, 0x3fb8aa3b
	s_mov_b32 s26, 0xc2ce8ed0
	s_mov_b32 s27, 0x42b17218
	s_mov_b32 s28, 0x7f800000
	s_mov_b32 s29, 0x3f2aaaab
	s_mov_b32 s33, 0x3f317218
	s_mov_b32 s50, 0x33800000
	s_mov_b32 s4, 0x11111111
	s_mov_b32 s5, 0x11111111
	s_mov_b32 s6, 1
	s_mov_b32 s7, 1
	v_mov_b32_e32 v168, 0x3ecc95a3
	v_mov_b32_e32 v171, 0x7f800000
	v_mov_b32_e32 v32, 0x3f317218
	v_mov_b32_e32 v31, 0x3a800000
	v_mov_b32_e32 v39, 0x358637bd
	v_mov_b32_e32 v30, 0x260
	s_cmp_lt_u32 s36, 0x10000
	s_cselect_b32 s40, s8, s10
	s_cselect_b32 s41, s9, s11
	s_and_b32 s42, s36, 0xffff
	s_mov_b32 s43, 0
	s_lshl_b64 s[42:43], s[42:43], 12
	s_add_u32 s40, s40, s42
	s_addc_u32 s41, s41, s43
	s_add_u32 s44, s40, 0x1000
	s_addc_u32 s45, s41, 0
	global_load_dwordx4 v[2:5], v1, s[40:41]
	global_load_dwordx4 v[6:9], v1, s[40:41] offset:1024
	global_load_dwordx4 v[10:13], v1, s[40:41] offset:2048
	global_load_dwordx4 v[14:17], v1, s[40:41] offset:3072
	global_load_dwordx4 v[180:183], v1, s[44:45]
	global_load_dwordx4 v[184:187], v1, s[44:45] offset:1024
	global_load_dwordx4 v[188:191], v1, s[44:45] offset:2048
	global_load_dwordx4 v[192:195], v1, s[44:45] offset:3072
	s_waitcnt vmcnt(8)
; __device__ __forceinline__ void p0_prologue(const Args& a, LAS unsigned char* lds, int gw, int NGW, int lane, int wave) {
;     ...
;     { const float* Win = a.in[I_WIN]; const float* pw = a.in[I_PREMIX];
; #pragma unroll
;       for (int j = 0; j < 8; ++j)
; #pragma unroll
;           for (int q = 0; q < 4; ++q)
; #pragma unroll
;               for (int e = 0; e < 4; ++e) { const int k = q * 256 + lane * 4 + e; wd[j][q * 4 + e] = Win[(size_t)k * 2056 + 1536 + j] * pw[k]; } }
	v_pk_mul_f32 v[40:41], v[40:41], v[196:197] op_sel:[0,0] op_sel_hi:[1,0]
	v_pk_mul_f32 v[42:43], v[42:43], v[196:197] op_sel:[0,0] op_sel_hi:[1,0]
	v_pk_mul_f32 v[44:45], v[44:45], v[196:197] op_sel:[0,0] op_sel_hi:[1,0]
	v_pk_mul_f32 v[46:47], v[46:47], v[196:197] op_sel:[0,0] op_sel_hi:[1,0]
	v_pk_mul_f32 v[48:49], v[48:49], v[196:197] op_sel:[0,1] op_sel_hi:[1,1]
	v_pk_mul_f32 v[50:51], v[50:51], v[196:197] op_sel:[0,1] op_sel_hi:[1,1]
	v_pk_mul_f32 v[52:53], v[52:53], v[196:197] op_sel:[0,1] op_sel_hi:[1,1]
	v_pk_mul_f32 v[54:55], v[54:55], v[196:197] op_sel:[0,1] op_sel_hi:[1,1]
	v_pk_mul_f32 v[56:57], v[56:57], v[198:199] op_sel:[0,0] op_sel_hi:[1,0]
	v_pk_mul_f32 v[58:59], v[58:59], v[198:199] op_sel:[0,0] op_sel_hi:[1,0]
	v_pk_mul_f32 v[60:61], v[60:61], v[198:199] op_sel:[0,0] op_sel_hi:[1,0]
	v_pk_mul_f32 v[62:63], v[62:63], v[198:199] op_sel:[0,0] op_sel_hi:[1,0]
	v_pk_mul_f32 v[64:65], v[64:65], v[198:199] op_sel:[0,1] op_sel_hi:[1,1]
	v_pk_mul_f32 v[66:67], v[66:67], v[198:199] op_sel:[0,1] op_sel_hi:[1,1]
	v_pk_mul_f32 v[68:69], v[68:69], v[198:199] op_sel:[0,1] op_sel_hi:[1,1]
	v_pk_mul_f32 v[70:71], v[70:71], v[198:199] op_sel:[0,1] op_sel_hi:[1,1]
	v_pk_mul_f32 v[72:73], v[72:73], v[200:201] op_sel:[0,0] op_sel_hi:[1,0]
	v_pk_mul_f32 v[74:75], v[74:75], v[200:201] op_sel:[0,0] op_sel_hi:[1,0]
	v_pk_mul_f32 v[76:77], v[76:77], v[200:201] op_sel:[0,0] op_sel_hi:[1,0]
	v_pk_mul_f32 v[78:79], v[78:79], v[200:201] op_sel:[0,0] op_sel_hi:[1,0]
	v_pk_mul_f32 v[80:81], v[80:81], v[200:201] op_sel:[0,1] op_sel_hi:[1,1]
	v_pk_mul_f32 v[82:83], v[82:83], v[200:201] op_sel:[0,1] op_sel_hi:[1,1]
	v_pk_mul_f32 v[84:85], v[84:85], v[200:201] op_sel:[0,1] op_sel_hi:[1,1]
	v_pk_mul_f32 v[86:87], v[86:87], v[200:201] op_sel:[0,1] op_sel_hi:[1,1]
	v_pk_mul_f32 v[88:89], v[88:89], v[202:203] op_sel:[0,0] op_sel_hi:[1,0]
	v_pk_mul_f32 v[90:91], v[90:91], v[202:203] op_sel:[0,0] op_sel_hi:[1,0]
	v_pk_mul_f32 v[92:93], v[92:93], v[202:203] op_sel:[0,0] op_sel_hi:[1,0]
	v_pk_mul_f32 v[94:95], v[94:95], v[202:203] op_sel:[0,0] op_sel_hi:[1,0]
	v_pk_mul_f32 v[96:97], v[96:97], v[202:203] op_sel:[0,1] op_sel_hi:[1,1]
	v_pk_mul_f32 v[98:99], v[98:99], v[202:203] op_sel:[0,1] op_sel_hi:[1,1]
	v_pk_mul_f32 v[100:101], v[100:101], v[202:203] op_sel:[0,1] op_sel_hi:[1,1]
	v_pk_mul_f32 v[102:103], v[102:103], v[202:203] op_sel:[0,1] op_sel_hi:[1,1]
	v_pk_mul_f32 v[104:105], v[104:105], v[204:205] op_sel:[0,0] op_sel_hi:[1,0]
	v_pk_mul_f32 v[106:107], v[106:107], v[204:205] op_sel:[0,0] op_sel_hi:[1,0]
	v_pk_mul_f32 v[108:109], v[108:109], v[204:205] op_sel:[0,0] op_sel_hi:[1,0]
	v_pk_mul_f32 v[110:111], v[110:111], v[204:205] op_sel:[0,0] op_sel_hi:[1,0]
	v_pk_mul_f32 v[112:113], v[112:113], v[204:205] op_sel:[0,1] op_sel_hi:[1,1]
	v_pk_mul_f32 v[114:115], v[114:115], v[204:205] op_sel:[0,1] op_sel_hi:[1,1]
	v_pk_mul_f32 v[116:117], v[116:117], v[204:205] op_sel:[0,1] op_sel_hi:[1,1]
	v_pk_mul_f32 v[118:119], v[118:119], v[204:205] op_sel:[0,1] op_sel_hi:[1,1]
	v_pk_mul_f32 v[120:121], v[120:121], v[206:207] op_sel:[0,0] op_sel_hi:[1,0]
	v_pk_mul_f32 v[122:123], v[122:123], v[206:207] op_sel:[0,0] op_sel_hi:[1,0]
	v_pk_mul_f32 v[124:125], v[124:125], v[206:207] op_sel:[0,0] op_sel_hi:[1,0]
	v_pk_mul_f32 v[126:127], v[126:127], v[206:207] op_sel:[0,0] op_sel_hi:[1,0]
	v_pk_mul_f32 v[128:129], v[128:129], v[206:207] op_sel:[0,1] op_sel_hi:[1,1]
	v_pk_mul_f32 v[130:131], v[130:131], v[206:207] op_sel:[0,1] op_sel_hi:[1,1]
	v_pk_mul_f32 v[132:133], v[132:133], v[206:207] op_sel:[0,1] op_sel_hi:[1,1]
	v_pk_mul_f32 v[134:135], v[134:135], v[206:207] op_sel:[0,1] op_sel_hi:[1,1]
	v_pk_mul_f32 v[136:137], v[136:137], v[208:209] op_sel:[0,0] op_sel_hi:[1,0]
	v_pk_mul_f32 v[138:139], v[138:139], v[208:209] op_sel:[0,0] op_sel_hi:[1,0]
	v_pk_mul_f32 v[140:141], v[140:141], v[208:209] op_sel:[0,0] op_sel_hi:[1,0]
	v_pk_mul_f32 v[142:143], v[142:143], v[208:209] op_sel:[0,0] op_sel_hi:[1,0]
	v_pk_mul_f32 v[144:145], v[144:145], v[208:209] op_sel:[0,1] op_sel_hi:[1,1]
	v_pk_mul_f32 v[146:147], v[146:147], v[208:209] op_sel:[0,1] op_sel_hi:[1,1]
	v_pk_mul_f32 v[148:149], v[148:149], v[208:209] op_sel:[0,1] op_sel_hi:[1,1]
	v_pk_mul_f32 v[150:151], v[150:151], v[208:209] op_sel:[0,1] op_sel_hi:[1,1]
	v_pk_mul_f32 v[152:153], v[152:153], v[210:211] op_sel:[0,0] op_sel_hi:[1,0]
	v_pk_mul_f32 v[154:155], v[154:155], v[210:211] op_sel:[0,0] op_sel_hi:[1,0]
	v_pk_mul_f32 v[156:157], v[156:157], v[210:211] op_sel:[0,0] op_sel_hi:[1,0]
	v_pk_mul_f32 v[158:159], v[158:159], v[210:211] op_sel:[0,0] op_sel_hi:[1,0]
	v_pk_mul_f32 v[160:161], v[160:161], v[210:211] op_sel:[0,1] op_sel_hi:[1,1]
	v_pk_mul_f32 v[162:163], v[162:163], v[210:211] op_sel:[0,1] op_sel_hi:[1,1]
	v_pk_mul_f32 v[164:165], v[164:165], v[210:211] op_sel:[0,1] op_sel_hi:[1,1]
	v_pk_mul_f32 v[166:167], v[166:167], v[210:211] op_sel:[0,1] op_sel_hi:[1,1]
	s_waitcnt vmcnt(4)
; __device__ __forceinline__ unsigned pk2(float lo, float hi) { f32x2 v; v.x = lo; v.y = hi; return __builtin_bit_cast(unsigned, __builtin_convertvector(v, hwbf2)); }
; __device__ __forceinline__ void p0_prologue(const Args& a, LAS unsigned char* lds, int gw, int NGW, int lane, int wave) {
;     ...
;     for (int row0 = 2 * gw; row0 < R; row0 += 2 * NGW) {
;         f32x4 vv[2][4];
; #pragma unroll
;         for (int rr = 0; rr < 2; ++rr) { const int row = row0 + rr;
;             const float* xr = row < RP ? a.in[I_XP] + (size_t)row * DM : a.in[I_XS] + (size_t)(row - RP) * DM;
; #pragma unroll
;             for (int q = 0; q < 4; ++q) vv[rr][q] = *(const f32x4*)(xr + q * 256 + lane * 4); }
; #pragma unroll
;         for (int rr = 0; rr < 2; ++rr) { const int row = row0 + rr;
;             float ss = 0.f;
; #pragma unroll
;             for (int q = 0; q < 4; ++q) { const f32x4 v = vv[rr][q]; ss += (v[0] * v[0] + v[1] * v[1]) + (v[2] * v[2] + v[3] * v[3]); }
;             ss = wave_sum(ss);
;             const float rs = 1.f / sqrtf(ss * (1.f / DM) + EPS);
; #pragma unroll
;             for (int q = 0; q < 4; ++q) { const f32x4 v = vv[rr][q]; u32x2 w; w.x = pk2(v[0], v[1]); w.y = pk2(v[2], v[3]); *(u32x2*)(xb + (size_t)row * DM + q * 256 + lane * 4) = w; }
;             float myd = 0.f;
; #pragma unroll
;             for (int j = 0; j < 8; ++j) { float d = 0.f;
; #pragma unroll
;                 for (int q = 0; q < 4; ++q)
; #pragma unroll
;                     for (int e = 0; e < 4; ++e) d += vv[rr][q][e] * wd[j][q * 4 + e];
.Lp0r_loop:
	s_lshl_b32 s46, s36, 11
	s_add_u32 s46, s46, 0x2400000
	s_add_u32 s46, s88, s46
	s_addc_u32 s47, s89, 0
	s_lshl_b32 s52, s36, 5
	s_add_u32 s52, s52, 0x300000
	s_add_u32 s52, s88, s52
	s_addc_u32 s53, s89, 0
	s_lshl_b32 s54, s36, 2
	s_add_u32 s54, s54, 0x100000
	s_add_u32 s54, s88, s54
	s_addc_u32 s55, s89, 0
	s_add_u32 s37, s36, s38
	s_cmp_lt_u32 s37, 0x10100
	s_cselect_b32 s37, s37, s36
	s_cmp_lt_u32 s37, 0x10000
	s_cselect_b32 s40, s8, s10
	s_cselect_b32 s41, s9, s11
	s_and_b32 s42, s37, 0xffff
	s_mov_b32 s43, 0
	s_lshl_b64 s[42:43], s[42:43], 12
	s_add_u32 s40, s40, s42
	s_addc_u32 s41, s41, s43
	s_add_u32 s44, s40, 0x1000
	s_addc_u32 s45, s41, 0
	s_waitcnt vmcnt(10)
	v_pk_mul_f32 v[196:197], v[2:3], v[40:41] op_sel:[0,0] op_sel_hi:[0,1]
	v_pk_mul_f32 v[198:199], v[2:3], v[42:43] op_sel:[0,0] op_sel_hi:[0,1]
	v_pk_mul_f32 v[200:201], v[2:3], v[44:45] op_sel:[0,0] op_sel_hi:[0,1]
	v_pk_mul_f32 v[212:213], v[2:3], v[2:3]
	v_pk_mul_f32 v[202:203], v[2:3], v[46:47] op_sel:[0,0] op_sel_hi:[0,1]
	v_pk_fma_f32 v[196:197], v[2:3], v[48:49], v[196:197] op_sel:[1,0,0] op_sel_hi:[1,1,1]
	v_pk_fma_f32 v[198:199], v[2:3], v[50:51], v[198:199] op_sel:[1,0,0] op_sel_hi:[1,1,1]
	v_pk_fma_f32 v[212:213], v[4:5], v[4:5], v[212:213]
	v_pk_fma_f32 v[200:201], v[2:3], v[52:53], v[200:201] op_sel:[1,0,0] op_sel_hi:[1,1,1]
	v_pk_fma_f32 v[202:203], v[2:3], v[54:55], v[202:203] op_sel:[1,0,0] op_sel_hi:[1,1,1]
	v_pk_fma_f32 v[196:197], v[4:5], v[56:57], v[196:197] op_sel:[0,0,0] op_sel_hi:[0,1,1]
	v_pk_fma_f32 v[212:213], v[6:7], v[6:7], v[212:213]
	v_pk_fma_f32 v[198:199], v[4:5], v[58:59], v[198:199] op_sel:[0,0,0] op_sel_hi:[0,1,1]
	v_pk_fma_f32 v[200:201], v[4:5], v[60:61], v[200:201] op_sel:[0,0,0] op_sel_hi:[0,1,1]
	v_pk_fma_f32 v[202:203], v[4:5], v[62:63], v[202:203] op_sel:[0,0,0] op_sel_hi:[0,1,1]
	v_pk_fma_f32 v[212:213], v[8:9], v[8:9], v[212:213]
	v_pk_fma_f32 v[196:197], v[4:5], v[64:65], v[196:197] op_sel:[1,0,0] op_sel_hi:[1,1,1]
	v_pk_fma_f32 v[198:199], v[4:5], v[66:67], v[198:199] op_sel:[1,0,0] op_sel_hi:[1,1,1]
	v_pk_fma_f32 v[200:201], v[4:5], v[68:69], v[200:201] op_sel:[1,0,0] op_sel_hi:[1,1,1]
	v_pk_fma_f32 v[212:213], v[10:11], v[10:11], v[212:213]
	v_pk_fma_f32 v[202:203], v[4:5], v[70:71], v[202:203] op_sel:[1,0,0] op_sel_hi:[1,1,1]
	v_pk_fma_f32 v[196:197], v[6:7], v[72:73], v[196:197] op_sel:[0,0,0] op_sel_hi:[0,1,1]
	v_pk_fma_f32 v[198:199], v[6:7], v[74:75], v[198:199] op_sel:[0,0,0] op_sel_hi:[0,1,1]
	v_pk_fma_f32 v[212:213], v[12:13], v[12:13], v[212:213]
	v_pk_fma_f32 v[200:201], v[6:7], v[76:77], v[200:201] op_sel:[0,0,0] op_sel_hi:[0,1,1]
	v_pk_fma_f32 v[202:203], v[6:7], v[78:79], v[202:203] op_sel:[0,0,0] op_sel_hi:[0,1,1]
	v_pk_fma_f32 v[196:197], v[6:7], v[80:81], v[196:197] op_sel:[1,0,0] op_sel_hi:[1,1,1]
	v_pk_fma_f32 v[212:213], v[14:15], v[14:15], v[212:213]
	v_pk_fma_f32 v[198:199], v[6:7], v[82:83], v[198:199] op_sel:[1,0,0] op_sel_hi:[1,1,1]
	v_pk_fma_f32 v[200:201], v[6:7], v[84:85], v[200:201] op_sel:[1,0,0] op_sel_hi:[1,1,1]
	v_pk_fma_f32 v[202:203], v[6:7], v[86:87], v[202:203] op_sel:[1,0,0] op_sel_hi:[1,1,1]
	v_pk_fma_f32 v[212:213], v[16:17], v[16:17], v[212:213]
	v_pk_fma_f32 v[196:197], v[8:9], v[88:89], v[196:197] op_sel:[0,0,0] op_sel_hi:[0,1,1]
	v_pk_fma_f32 v[198:199], v[8:9], v[90:91], v[198:199] op_sel:[0,0,0] op_sel_hi:[0,1,1]
	v_pk_fma_f32 v[200:201], v[8:9], v[92:93], v[200:201] op_sel:[0,0,0] op_sel_hi:[0,1,1]
	v_cvt_pk_bf16_f32 v216, v2, v3
	v_pk_fma_f32 v[202:203], v[8:9], v[94:95], v[202:203] op_sel:[0,0,0] op_sel_hi:[0,1,1]
	v_pk_fma_f32 v[196:197], v[8:9], v[96:97], v[196:197] op_sel:[1,0,0] op_sel_hi:[1,1,1]
	v_pk_fma_f32 v[198:199], v[8:9], v[98:99], v[198:199] op_sel:[1,0,0] op_sel_hi:[1,1,1]
	v_cvt_pk_bf16_f32 v217, v4, v5
	v_pk_fma_f32 v[200:201], v[8:9], v[100:101], v[200:201] op_sel:[1,0,0] op_sel_hi:[1,1,1]
	v_pk_fma_f32 v[202:203], v[8:9], v[102:103], v[202:203] op_sel:[1,0,0] op_sel_hi:[1,1,1]
	v_pk_fma_f32 v[196:197], v[10:11], v[104:105], v[196:197] op_sel:[0,0,0] op_sel_hi:[0,1,1]
	global_store_dwordx2 v38, v[216:217], s[46:47]
	v_pk_fma_f32 v[198:199], v[10:11], v[106:107], v[198:199] op_sel:[0,0,0] op_sel_hi:[0,1,1]
	v_pk_fma_f32 v[200:201], v[10:11], v[108:109], v[200:201] op_sel:[0,0,0] op_sel_hi:[0,1,1]
	v_pk_fma_f32 v[202:203], v[10:11], v[110:111], v[202:203] op_sel:[0,0,0] op_sel_hi:[0,1,1]
	v_cvt_pk_bf16_f32 v218, v6, v7
	v_pk_fma_f32 v[196:197], v[10:11], v[112:113], v[196:197] op_sel:[1,0,0] op_sel_hi:[1,1,1]
	v_pk_fma_f32 v[198:199], v[10:11], v[114:115], v[198:199] op_sel:[1,0,0] op_sel_hi:[1,1,1]
	v_pk_fma_f32 v[200:201], v[10:11], v[116:117], v[200:201] op_sel:[1,0,0] op_sel_hi:[1,1,1]
	v_cvt_pk_bf16_f32 v219, v8, v9
	v_pk_fma_f32 v[202:203], v[10:11], v[118:119], v[202:203] op_sel:[1,0,0] op_sel_hi:[1,1,1]
	v_pk_fma_f32 v[196:197], v[12:13], v[120:121], v[196:197] op_sel:[0,0,0] op_sel_hi:[0,1,1]
	v_pk_fma_f32 v[198:199], v[12:13], v[122:123], v[198:199] op_sel:[0,0,0] op_sel_hi:[0,1,1]
	global_store_dwordx2 v38, v[218:219], s[46:47] offset:512
	v_pk_fma_f32 v[200:201], v[12:13], v[124:125], v[200:201] op_sel:[0,0,0] op_sel_hi:[0,1,1]
	v_pk_fma_f32 v[202:203], v[12:13], v[126:127], v[202:203] op_sel:[0,0,0] op_sel_hi:[0,1,1]
	v_pk_fma_f32 v[196:197], v[12:13], v[128:129], v[196:197] op_sel:[1,0,0] op_sel_hi:[1,1,1]
	v_cvt_pk_bf16_f32 v220, v10, v11
	v_pk_fma_f32 v[198:199], v[12:13], v[130:131], v[198:199] op_sel:[1,0,0] op_sel_hi:[1,1,1]
	v_pk_fma_f32 v[200:201], v[12:13], v[132:133], v[200:201] op_sel:[1,0,0] op_sel_hi:[1,1,1]
	v_pk_fma_f32 v[202:203], v[12:13], v[134:135], v[202:203] op_sel:[1,0,0] op_sel_hi:[1,1,1]
	v_cvt_pk_bf16_f32 v221, v12, v13
; __device__ __forceinline__ unsigned pk2(float lo, float hi) { f32x2 v; v.x = lo; v.y = hi; return __builtin_bit_cast(unsigned, __builtin_convertvector(v, hwbf2)); }
; __device__ __forceinline__ void p0_prologue(const Args& a, LAS unsigned char* lds, int gw, int NGW, int lane, int wave) {
;     ...
;         for (int rr = 0; rr < 2; ++rr) { const int row = row0 + rr;
;             const float* xr = row < RP ? a.in[I_XP] + (size_t)row * DM : a.in[I_XS] + (size_t)(row - RP) * DM;
; #pragma unroll
;             for (int q = 0; q < 4; ++q) vv[rr][q] = *(const f32x4*)(xr + q * 256 + lane * 4); }
; #pragma unroll
;         for (int rr = 0; rr < 2; ++rr) { const int row = row0 + rr;
;             float ss = 0.f;
; #pragma unroll
;             for (int q = 0; q < 4; ++q) { const f32x4 v = vv[rr][q]; ss += (v[0] * v[0] + v[1] * v[1]) + (v[2] * v[2] + v[3] * v[3]); }
;             ss = wave_sum(ss);
;             const float rs = 1.f / sqrtf(ss * (1.f / DM) + EPS);
; #pragma unroll
;             for (int q = 0; q < 4; ++q) { const f32x4 v = vv[rr][q]; u32x2 w; w.x = pk2(v[0], v[1]); w.y = pk2(v[2], v[3]); *(u32x2*)(xb + (size_t)row * DM + q * 256 + lane * 4) = w; }
;             float myd = 0.f;
; #pragma unroll
;             for (int j = 0; j < 8; ++j) { float d = 0.f;
; #pragma unroll
;                 for (int q = 0; q < 4; ++q)
; #pragma unroll
;                     for (int e = 0; e < 4; ++e) d += vv[rr][q][e] * wd[j][q * 4 + e];
;                 d = wave_sum(d);
;                 if (lane == j) myd = d; }
	v_pk_fma_f32 v[196:197], v[14:15], v[136:137], v[196:197] op_sel:[0,0,0] op_sel_hi:[0,1,1]
	v_pk_fma_f32 v[198:199], v[14:15], v[138:139], v[198:199] op_sel:[0,0,0] op_sel_hi:[0,1,1]
	v_pk_fma_f32 v[200:201], v[14:15], v[140:141], v[200:201] op_sel:[0,0,0] op_sel_hi:[0,1,1]
	global_store_dwordx2 v38, v[220:221], s[46:47] offset:1024
	v_pk_fma_f32 v[202:203], v[14:15], v[142:143], v[202:203] op_sel:[0,0,0] op_sel_hi:[0,1,1]
	v_pk_fma_f32 v[196:197], v[14:15], v[144:145], v[196:197] op_sel:[1,0,0] op_sel_hi:[1,1,1]
	v_pk_fma_f32 v[198:199], v[14:15], v[146:147], v[198:199] op_sel:[1,0,0] op_sel_hi:[1,1,1]
	v_cvt_pk_bf16_f32 v222, v14, v15
	v_pk_fma_f32 v[200:201], v[14:15], v[148:149], v[200:201] op_sel:[1,0,0] op_sel_hi:[1,1,1]
	v_pk_fma_f32 v[202:203], v[14:15], v[150:151], v[202:203] op_sel:[1,0,0] op_sel_hi:[1,1,1]
	v_pk_fma_f32 v[196:197], v[16:17], v[152:153], v[196:197] op_sel:[0,0,0] op_sel_hi:[0,1,1]
	v_cvt_pk_bf16_f32 v223, v16, v17
	v_pk_fma_f32 v[198:199], v[16:17], v[154:155], v[198:199] op_sel:[0,0,0] op_sel_hi:[0,1,1]
	v_pk_fma_f32 v[200:201], v[16:17], v[156:157], v[200:201] op_sel:[0,0,0] op_sel_hi:[0,1,1]
	v_pk_fma_f32 v[202:203], v[16:17], v[158:159], v[202:203] op_sel:[0,0,0] op_sel_hi:[0,1,1]
	global_store_dwordx2 v38, v[222:223], s[46:47] offset:1536
	v_pk_fma_f32 v[196:197], v[16:17], v[160:161], v[196:197] op_sel:[1,0,0] op_sel_hi:[1,1,1]
	v_pk_fma_f32 v[198:199], v[16:17], v[162:163], v[198:199] op_sel:[1,0,0] op_sel_hi:[1,1,1]
	v_pk_fma_f32 v[200:201], v[16:17], v[164:165], v[200:201] op_sel:[1,0,0] op_sel_hi:[1,1,1]
	v_pk_fma_f32 v[202:203], v[16:17], v[166:167], v[202:203] op_sel:[1,0,0] op_sel_hi:[1,1,1]
	global_load_dwordx4 v[2:5], v1, s[40:41]
	global_load_dwordx4 v[6:9], v1, s[40:41] offset:1024
	global_load_dwordx4 v[10:13], v1, s[40:41] offset:2048
	global_load_dwordx4 v[14:17], v1, s[40:41] offset:3072
	v_add_f32_e32 v212, v212, v213
	s_waitcnt vmcnt(8)
	v_pk_mul_f32 v[204:205], v[180:181], v[40:41] op_sel:[0,0] op_sel_hi:[0,1]
	v_pk_mul_f32 v[206:207], v[180:181], v[42:43] op_sel:[0,0] op_sel_hi:[0,1]
	v_pk_mul_f32 v[208:209], v[180:181], v[44:45] op_sel:[0,0] op_sel_hi:[0,1]
	v_pk_mul_f32 v[214:215], v[180:181], v[180:181]
	v_pk_mul_f32 v[210:211], v[180:181], v[46:47] op_sel:[0,0] op_sel_hi:[0,1]
	v_pk_fma_f32 v[204:205], v[180:181], v[48:49], v[204:205] op_sel:[1,0,0] op_sel_hi:[1,1,1]
	v_pk_fma_f32 v[206:207], v[180:181], v[50:51], v[206:207] op_sel:[1,0,0] op_sel_hi:[1,1,1]
	v_pk_fma_f32 v[214:215], v[182:183], v[182:183], v[214:215]
	v_pk_fma_f32 v[208:209], v[180:181], v[52:53], v[208:209] op_sel:[1,0,0] op_sel_hi:[1,1,1]
	v_pk_fma_f32 v[210:211], v[180:181], v[54:55], v[210:211] op_sel:[1,0,0] op_sel_hi:[1,1,1]
	v_pk_fma_f32 v[204:205], v[182:183], v[56:57], v[204:205] op_sel:[0,0,0] op_sel_hi:[0,1,1]
	v_pk_fma_f32 v[214:215], v[184:185], v[184:185], v[214:215]
	v_pk_fma_f32 v[206:207], v[182:183], v[58:59], v[206:207] op_sel:[0,0,0] op_sel_hi:[0,1,1]
	v_pk_fma_f32 v[208:209], v[182:183], v[60:61], v[208:209] op_sel:[0,0,0] op_sel_hi:[0,1,1]
	v_pk_fma_f32 v[210:211], v[182:183], v[62:63], v[210:211] op_sel:[0,0,0] op_sel_hi:[0,1,1]
	v_pk_fma_f32 v[214:215], v[186:187], v[186:187], v[214:215]
	v_pk_fma_f32 v[204:205], v[182:183], v[64:65], v[204:205] op_sel:[1,0,0] op_sel_hi:[1,1,1]
	v_pk_fma_f32 v[206:207], v[182:183], v[66:67], v[206:207] op_sel:[1,0,0] op_sel_hi:[1,1,1]
	v_pk_fma_f32 v[208:209], v[182:183], v[68:69], v[208:209] op_sel:[1,0,0] op_sel_hi:[1,1,1]
	v_pk_fma_f32 v[214:215], v[188:189], v[188:189], v[214:215]
	v_pk_fma_f32 v[210:211], v[182:183], v[70:71], v[210:211] op_sel:[1,0,0] op_sel_hi:[1,1,1]
	v_pk_fma_f32 v[204:205], v[184:185], v[72:73], v[204:205] op_sel:[0,0,0] op_sel_hi:[0,1,1]
	v_pk_fma_f32 v[206:207], v[184:185], v[74:75], v[206:207] op_sel:[0,0,0] op_sel_hi:[0,1,1]
	v_pk_fma_f32 v[214:215], v[190:191], v[190:191], v[214:215]
	v_pk_fma_f32 v[208:209], v[184:185], v[76:77], v[208:209] op_sel:[0,0,0] op_sel_hi:[0,1,1]
	v_pk_fma_f32 v[210:211], v[184:185], v[78:79], v[210:211] op_sel:[0,0,0] op_sel_hi:[0,1,1]
	v_pk_fma_f32 v[204:205], v[184:185], v[80:81], v[204:205] op_sel:[1,0,0] op_sel_hi:[1,1,1]
	v_pk_fma_f32 v[214:215], v[192:193], v[192:193], v[214:215]
	v_pk_fma_f32 v[206:207], v[184:185], v[82:83], v[206:207] op_sel:[1,0,0] op_sel_hi:[1,1,1]
	v_pk_fma_f32 v[208:209], v[184:185], v[84:85], v[208:209] op_sel:[1,0,0] op_sel_hi:[1,1,1]
	v_pk_fma_f32 v[210:211], v[184:185], v[86:87], v[210:211] op_sel:[1,0,0] op_sel_hi:[1,1,1]
	v_pk_fma_f32 v[214:215], v[194:195], v[194:195], v[214:215]
	v_pk_fma_f32 v[204:205], v[186:187], v[88:89], v[204:205] op_sel:[0,0,0] op_sel_hi:[0,1,1]
	v_pk_fma_f32 v[206:207], v[186:187], v[90:91], v[206:207] op_sel:[0,0,0] op_sel_hi:[0,1,1]
	v_pk_fma_f32 v[208:209], v[186:187], v[92:93], v[208:209] op_sel:[0,0,0] op_sel_hi:[0,1,1]
	v_cvt_pk_bf16_f32 v216, v180, v181
	v_pk_fma_f32 v[210:211], v[186:187], v[94:95], v[210:211] op_sel:[0,0,0] op_sel_hi:[0,1,1]
	v_pk_fma_f32 v[204:205], v[186:187], v[96:97], v[204:205] op_sel:[1,0,0] op_sel_hi:[1,1,1]
	v_pk_fma_f32 v[206:207], v[186:187], v[98:99], v[206:207] op_sel:[1,0,0] op_sel_hi:[1,1,1]
	v_cvt_pk_bf16_f32 v217, v182, v183
	v_pk_fma_f32 v[208:209], v[186:187], v[100:101], v[208:209] op_sel:[1,0,0] op_sel_hi:[1,1,1]
	v_pk_fma_f32 v[210:211], v[186:187], v[102:103], v[210:211] op_sel:[1,0,0] op_sel_hi:[1,1,1]
	v_pk_fma_f32 v[204:205], v[188:189], v[104:105], v[204:205] op_sel:[0,0,0] op_sel_hi:[0,1,1]
	global_store_dwordx2 v38, v[216:217], s[46:47] offset:2048
	v_pk_fma_f32 v[206:207], v[188:189], v[106:107], v[206:207] op_sel:[0,0,0] op_sel_hi:[0,1,1]
; __device__ __forceinline__ unsigned pk2(float lo, float hi) { f32x2 v; v.x = lo; v.y = hi; return __builtin_bit_cast(unsigned, __builtin_convertvector(v, hwbf2)); }
; template <int CTRL, int RM> __device__ __forceinline__ float dpp_get(float v) { return __builtin_bit_cast(float, __builtin_amdgcn_update_dpp(0, __builtin_bit_cast(int, v), CTRL, RM, 0xF, false)); }
; __device__ __forceinline__ float wave_sum(float v) {
;     v += dpp_get<0xB1, 0xF>(v);
;     v += dpp_get<0x4E, 0xF>(v);
;     v += dpp_get<0x141, 0xF>(v);
;     v += dpp_get<0x140, 0xF>(v);
;     v += dpp_get<0x142, 0xA>(v);
;     v += dpp_get<0x143, 0xC>(v);
;     return __builtin_bit_cast(float, __builtin_amdgcn_readlane(__builtin_bit_cast(int, v), 63));
; }
; __device__ __forceinline__ void p0_prologue(const Args& a, LAS unsigned char* lds, int gw, int NGW, int lane, int wave) {
;     ...
;             ss = wave_sum(ss);
;             const float rs = 1.f / sqrtf(ss * (1.f / DM) + EPS);
; #pragma unroll
;             for (int q = 0; q < 4; ++q) { const f32x4 v = vv[rr][q]; u32x2 w; w.x = pk2(v[0], v[1]); w.y = pk2(v[2], v[3]); *(u32x2*)(xb + (size_t)row * DM + q * 256 + lane * 4) = w; }
;             float myd = 0.f;
; #pragma unroll
;             for (int j = 0; j < 8; ++j) { float d = 0.f;
; #pragma unroll
;                 for (int q = 0; q < 4; ++q)
; #pragma unroll
;                     for (int e = 0; e < 4; ++e) d += vv[rr][q][e] * wd[j][q * 4 + e];
;                 d = wave_sum(d);
;                 if (lane == j) myd = d; }
;             if (lane < 8) { const float xx = myd * rs + dtb[lane]; dtv[(size_t)row * 8 + lane] = xx > 20.f ? xx : log1pf(expf(xx)); }
;             if (lane == 0) rstd1[row] = rs; }
	v_pk_fma_f32 v[208:209], v[188:189], v[108:109], v[208:209] op_sel:[0,0,0] op_sel_hi:[0,1,1]
	v_pk_fma_f32 v[210:211], v[188:189], v[110:111], v[210:211] op_sel:[0,0,0] op_sel_hi:[0,1,1]
	v_cvt_pk_bf16_f32 v218, v184, v185
	v_pk_fma_f32 v[204:205], v[188:189], v[112:113], v[204:205] op_sel:[1,0,0] op_sel_hi:[1,1,1]
	v_pk_fma_f32 v[206:207], v[188:189], v[114:115], v[206:207] op_sel:[1,0,0] op_sel_hi:[1,1,1]
	v_pk_fma_f32 v[208:209], v[188:189], v[116:117], v[208:209] op_sel:[1,0,0] op_sel_hi:[1,1,1]
	v_cvt_pk_bf16_f32 v219, v186, v187
	v_pk_fma_f32 v[210:211], v[188:189], v[118:119], v[210:211] op_sel:[1,0,0] op_sel_hi:[1,1,1]
	v_pk_fma_f32 v[204:205], v[190:191], v[120:121], v[204:205] op_sel:[0,0,0] op_sel_hi:[0,1,1]
	v_pk_fma_f32 v[206:207], v[190:191], v[122:123], v[206:207] op_sel:[0,0,0] op_sel_hi:[0,1,1]
	global_store_dwordx2 v38, v[218:219], s[46:47] offset:2560
	v_pk_fma_f32 v[208:209], v[190:191], v[124:125], v[208:209] op_sel:[0,0,0] op_sel_hi:[0,1,1]
	v_pk_fma_f32 v[210:211], v[190:191], v[126:127], v[210:211] op_sel:[0,0,0] op_sel_hi:[0,1,1]
	v_pk_fma_f32 v[204:205], v[190:191], v[128:129], v[204:205] op_sel:[1,0,0] op_sel_hi:[1,1,1]
	v_cvt_pk_bf16_f32 v220, v188, v189
	v_pk_fma_f32 v[206:207], v[190:191], v[130:131], v[206:207] op_sel:[1,0,0] op_sel_hi:[1,1,1]
	v_pk_fma_f32 v[208:209], v[190:191], v[132:133], v[208:209] op_sel:[1,0,0] op_sel_hi:[1,1,1]
	v_pk_fma_f32 v[210:211], v[190:191], v[134:135], v[210:211] op_sel:[1,0,0] op_sel_hi:[1,1,1]
	v_cvt_pk_bf16_f32 v221, v190, v191
	v_pk_fma_f32 v[204:205], v[192:193], v[136:137], v[204:205] op_sel:[0,0,0] op_sel_hi:[0,1,1]
	v_pk_fma_f32 v[206:207], v[192:193], v[138:139], v[206:207] op_sel:[0,0,0] op_sel_hi:[0,1,1]
	v_pk_fma_f32 v[208:209], v[192:193], v[140:141], v[208:209] op_sel:[0,0,0] op_sel_hi:[0,1,1]
	global_store_dwordx2 v38, v[220:221], s[46:47] offset:3072
	v_pk_fma_f32 v[210:211], v[192:193], v[142:143], v[210:211] op_sel:[0,0,0] op_sel_hi:[0,1,1]
	v_pk_fma_f32 v[204:205], v[192:193], v[144:145], v[204:205] op_sel:[1,0,0] op_sel_hi:[1,1,1]
	v_pk_fma_f32 v[206:207], v[192:193], v[146:147], v[206:207] op_sel:[1,0,0] op_sel_hi:[1,1,1]
	v_cvt_pk_bf16_f32 v222, v192, v193
	v_pk_fma_f32 v[208:209], v[192:193], v[148:149], v[208:209] op_sel:[1,0,0] op_sel_hi:[1,1,1]
	v_pk_fma_f32 v[210:211], v[192:193], v[150:151], v[210:211] op_sel:[1,0,0] op_sel_hi:[1,1,1]
	v_pk_fma_f32 v[204:205], v[194:195], v[152:153], v[204:205] op_sel:[0,0,0] op_sel_hi:[0,1,1]
	v_cvt_pk_bf16_f32 v223, v194, v195
	v_pk_fma_f32 v[206:207], v[194:195], v[154:155], v[206:207] op_sel:[0,0,0] op_sel_hi:[0,1,1]
	v_pk_fma_f32 v[208:209], v[194:195], v[156:157], v[208:209] op_sel:[0,0,0] op_sel_hi:[0,1,1]
	v_pk_fma_f32 v[210:211], v[194:195], v[158:159], v[210:211] op_sel:[0,0,0] op_sel_hi:[0,1,1]
	global_store_dwordx2 v38, v[222:223], s[46:47] offset:3584
	v_pk_fma_f32 v[204:205], v[194:195], v[160:161], v[204:205] op_sel:[1,0,0] op_sel_hi:[1,1,1]
	v_pk_fma_f32 v[206:207], v[194:195], v[162:163], v[206:207] op_sel:[1,0,0] op_sel_hi:[1,1,1]
	v_pk_fma_f32 v[208:209], v[194:195], v[164:165], v[208:209] op_sel:[1,0,0] op_sel_hi:[1,1,1]
	v_pk_fma_f32 v[210:211], v[194:195], v[166:167], v[210:211] op_sel:[1,0,0] op_sel_hi:[1,1,1]
	global_load_dwordx4 v[180:183], v1, s[44:45]
	global_load_dwordx4 v[184:187], v1, s[44:45] offset:1024
	global_load_dwordx4 v[188:191], v1, s[44:45] offset:2048
	global_load_dwordx4 v[192:195], v1, s[44:45] offset:3072
	v_add_f32_e32 v214, v214, v215
	s_nop 1
	v_permlane32_swap_b32_e32 v196, v204
	v_permlane32_swap_b32_e32 v197, v205
	v_permlane32_swap_b32_e32 v198, v206
	v_permlane32_swap_b32_e32 v199, v207
	v_permlane32_swap_b32_e32 v200, v208
	v_permlane32_swap_b32_e32 v201, v209
	v_permlane32_swap_b32_e32 v202, v210
	v_permlane32_swap_b32_e32 v203, v211
	v_permlane32_swap_b32_e32 v212, v214
	v_add_f32_e32 v196, v196, v204
	v_add_f32_e32 v197, v197, v205
	v_add_f32_e32 v198, v198, v206
	v_add_f32_e32 v199, v199, v207
	v_add_f32_e32 v200, v200, v208
	v_add_f32_e32 v201, v201, v209
	v_add_f32_e32 v202, v202, v210
	v_add_f32_e32 v203, v203, v211
	v_add_f32_e32 v212, v212, v214
	s_nop 0
	v_permlane16_swap_b32_e32 v196, v197
	v_permlane16_swap_b32_e32 v198, v199
	v_permlane16_swap_b32_e32 v200, v201
	v_permlane16_swap_b32_e32 v202, v203
	v_add_f32_e32 v196, v196, v197
	v_add_f32_e32 v198, v198, v199
	v_add_f32_e32 v200, v200, v201
	v_add_f32_e32 v202, v202, v203
	v_add_f32_dpp v212, v212, v212 quad_perm:[1,0,3,2] row_mask:0xf bank_mask:0xf
	s_nop 0
	v_add_f32_dpp v204, v196, v196 row_ror:8 row_mask:0xf bank_mask:0xf
	v_add_f32_dpp v205, v200, v200 row_ror:8 row_mask:0xf bank_mask:0xf
	v_add_f32_dpp v212, v212, v212 quad_perm:[2,3,0,1] row_mask:0xf bank_mask:0xf
	v_add_f32_dpp v204, v198, v198 row_ror:8 row_mask:0xf bank_mask:0xc
	v_add_f32_dpp v205, v202, v202 row_ror:8 row_mask:0xf bank_mask:0xc
	v_add_f32_dpp v212, v212, v212 row_half_mirror row_mask:0xf bank_mask:0xf
	s_nop 0
	v_add_f32_dpp v206, v204, v204 row_half_mirror row_mask:0xf bank_mask:0xf
	s_nop 0
	v_add_f32_dpp v212, v212, v212 row_mirror row_mask:0xf bank_mask:0xf
	v_add_f32_dpp v206, v205, v205 row_half_mirror row_mask:0xf bank_mask:0xa
	s_nop 0
	v_mov_b32_e32 v213, v212
	v_add_f32_dpp v206, v206, v206 quad_perm:[1,0,3,2] row_mask:0xf bank_mask:0xf
	s_nop 1
	v_permlane16_swap_b32_e32 v212, v213
	v_add_f32_dpp v206, v206, v206 quad_perm:[2,3,0,1] row_mask:0xf bank_mask:0xf
	v_add_f32_e32 v212, v212, v213
	v_fma_f32 v26, v212, v31, v39
	v_mul_f32_e32 v27, 0x4f800000, v26
	v_cmp_gt_f32_e32 vcc, s18, v26
	s_nop 1
	v_cndmask_b32_e32 v28, v26, v27, vcc
	v_sqrt_f32_e32 v29, v28
	s_nop 0
	v_add_u32_e32 v26, -1, v29
	v_fma_f32 v27, -v26, v29, v28
	v_cmp_ge_f32_e64 s[24:25], 0, v27
	v_add_u32_e32 v27, 1, v29
	s_nop 0
	v_cndmask_b32_e64 v26, v29, v26, s[24:25]
	v_fma_f32 v29, -v27, v29, v28
	v_cmp_lt_f32_e64 s[24:25], 0, v29
	s_nop 1
	v_cndmask_b32_e64 v26, v26, v27, s[24:25]
	v_mul_f32_e32 v27, 0x37800000, v26
	v_cndmask_b32_e32 v26, v26, v27, vcc
	v_cmp_class_f32_e32 vcc, v28, v30
	s_nop 1
	v_cndmask_b32_e32 v26, v26, v28, vcc
	v_div_scale_f32 v27, s[24:25], v26, v26, 1.0
	v_rcp_f32_e32 v29, v27
	s_nop 0
	v_fma_f32 v28, -v27, v29, 1.0
	v_fmac_f32_e32 v29, v28, v29
	v_div_scale_f32 v28, vcc, 1.0, v26, 1.0
	v_mul_f32_e32 v216, v28, v29
	v_fma_f32 v217, -v27, v216, v28
	v_fmac_f32_e32 v216, v217, v29
	v_fma_f32 v28, -v27, v216, v28
	s_nop 0
	v_div_fmas_f32 v28, v28, v29, v216
	v_div_fixup_f32 v224, v28, v26, 1.0
	s_mov_b64 exec, s[6:7]
	global_store_dword v35, v224, s[54:55]
	s_mov_b64 exec, -1
	v_mov_b32_e32 v19, v18
	v_fmac_f32_e32 v19, v224, v206
	v_cmp_nlt_f32_e32 vcc, s19, v19
	s_and_saveexec_b64 s[48:49], vcc
	s_cbranch_execz .Lp0r_sp_done
; __device__ __forceinline__ void p0_prologue(const Args& a, LAS unsigned char* lds, int gw, int NGW, int lane, int wave) {
;     ...
;             if (lane < 8) { const float xx = myd * rs + dtb[lane]; dtv[(size_t)row * 8 + lane] = xx > 20.f ? xx : log1pf(expf(xx)); }
;             if (lane == 0) rstd1[row] = rs; }
;     }
	v_mul_f32_e32 v20, 0x3fb8aa3b, v19
	v_rndne_f32_e32 v21, v20
	v_sub_f32_e32 v22, v20, v21
	v_fma_f32 v20, v19, s23, -v20
	v_fmac_f32_e32 v20, 0x32a5705f, v19
	v_add_f32_e32 v20, v22, v20
	v_cvt_i32_f32_e32 v21, v21
	v_exp_f32_e32 v20, v20
	v_cmp_ngt_f32_e32 vcc, s26, v19
	v_ldexp_f32 v20, v20, v21
	s_nop 0
	v_cndmask_b32_e32 v20, 0, v20, vcc
	v_cmp_nlt_f32_e32 vcc, s27, v19
	s_nop 1
	v_cndmask_b32_e32 v19, v171, v20, vcc
	v_add_f32_e32 v22, 1.0, v19
	v_add_f32_e32 v20, -1.0, v22
	v_sub_f32_e32 v21, v20, v22
	v_add_f32_e32 v21, 1.0, v21
	v_sub_f32_e32 v20, v19, v20
	v_add_f32_e32 v23, v20, v21
	v_frexp_mant_f32_e32 v24, v22
	v_cvt_f64_f32_e32 v[20:21], v22
	v_frexp_exp_i32_f64_e32 v20, v[20:21]
	v_cmp_gt_f32_e32 vcc, s29, v24
	s_nop 1
	v_subbrev_co_u32_e32 v172, vcc, 0, v20, vcc
	v_sub_u32_e32 v20, 0, v172
	v_ldexp_f32 v21, v22, v20
	v_add_f32_e32 v22, -1.0, v21
	v_add_f32_e32 v24, 1.0, v21
	v_ldexp_f32 v20, v23, v20
	v_add_f32_e32 v23, 1.0, v22
	v_add_f32_e32 v25, -1.0, v24
	v_sub_f32_e32 v23, v21, v23
	v_sub_f32_e32 v21, v21, v25
	v_add_f32_e32 v23, v20, v23
	v_add_f32_e32 v20, v20, v21
	v_add_f32_e32 v33, v24, v20
	v_rcp_f32_e32 v174, v33
	v_sub_f32_e32 v21, v24, v33
	v_add_f32_e32 v173, v20, v21
	v_add_f32_e32 v21, v22, v23
	v_mul_f32_e32 v178, v21, v174
	v_sub_f32_e32 v20, v22, v21
	v_mul_f32_e32 v22, v33, v178
	v_fma_f32 v24, v178, v33, -v22
	v_fmac_f32_e32 v24, v178, v173
	v_add_f32_e32 v175, v23, v20
	v_add_f32_e32 v20, v22, v24
	v_sub_f32_e32 v23, v21, v20
	v_pk_add_f32 v[36:37], v[20:21], v[22:23] neg_lo:[0,1] neg_hi:[0,1]
	v_mov_b32_e32 v25, v20
	v_pk_add_f32 v[20:21], v[36:37], v[24:25] neg_lo:[0,1] neg_hi:[0,1]
	v_cmp_neq_f32_e32 vcc, s28, v19
	v_add_f32_e32 v21, v175, v21
	v_add_f32_e32 v20, v20, v21
	v_add_f32_e32 v21, v23, v20
	v_mul_f32_e32 v175, v174, v21
	v_mul_f32_e32 v22, v33, v175
	v_fma_f32 v24, v175, v33, -v22
	v_fmac_f32_e32 v24, v175, v173
	v_sub_f32_e32 v23, v23, v21
	v_add_f32_e32 v33, v20, v23
	v_add_f32_e32 v20, v22, v24
	v_sub_f32_e32 v23, v21, v20
	v_pk_add_f32 v[36:37], v[20:21], v[22:23] neg_lo:[0,1] neg_hi:[0,1]
	v_mov_b32_e32 v25, v20
	v_pk_add_f32 v[20:21], v[36:37], v[24:25] neg_lo:[0,1] neg_hi:[0,1]
	s_nop 0
	v_add_f32_e32 v21, v33, v21
	v_add_f32_e32 v20, v20, v21
	v_add_f32_e32 v21, v178, v175
	v_add_f32_e32 v20, v23, v20
	v_sub_f32_e32 v22, v21, v178
	v_mul_f32_e32 v20, v174, v20
	v_sub_f32_e32 v22, v175, v22
	v_add_f32_e32 v22, v22, v20
	v_add_f32_e32 v24, v21, v22
	v_mul_f32_e32 v25, v24, v24
	v_fmamk_f32 v20, v25, 0x3e9b6dac, v168
	v_fmaak_f32 v33, v25, v20, 0x3f2aaada
	v_cvt_f32_i32_e32 v20, v172
	v_sub_f32_e32 v21, v24, v21
	v_sub_f32_e32 v21, v22, v21
	v_ldexp_f32 v36, v21, 1
	v_mul_f32_e32 v21, v24, v25
	v_ldexp_f32 v23, v24, 1
	v_pk_mul_f32 v[24:25], v[20:21], v[32:33]
	s_nop 0
	v_fma_f32 v22, v20, s33, -v24
	v_fmac_f32_e32 v22, 0xb102e308, v20
	v_pk_add_f32 v[20:21], v[24:25], v[22:23]
	s_nop 0
	v_sub_f32_e32 v23, v21, v23
	v_sub_f32_e32 v23, v25, v23
	v_add_f32_e32 v37, v36, v23
	v_mov_b32_e32 v36, v24
	v_pk_add_f32 v[24:25], v[20:21], v[24:25] neg_lo:[0,1] neg_hi:[0,1]
	v_pk_add_f32 v[172:173], v[20:21], v[36:37]
	v_mov_b32_e32 v23, v20
	v_mov_b32_e32 v25, v173
	v_pk_add_f32 v[174:175], v[22:23], v[24:25] neg_lo:[0,1] neg_hi:[0,1]
	v_pk_add_f32 v[22:23], v[22:23], v[24:25]
	v_mov_b32_e32 v36, v37
	v_pk_add_f32 v[24:25], v[22:23], v[20:21] op_sel:[1,0] op_sel_hi:[0,1] neg_lo:[0,1] neg_hi:[0,1]
	v_pk_add_f32 v[178:179], v[172:173], v[24:25] op_sel_hi:[1,0] neg_lo:[0,1] neg_hi:[0,1]
	v_mov_b32_e32 v172, v173
	v_mov_b32_e32 v173, v23
	v_pk_mov_b32 v[24:25], v[20:21], v[24:25] op_sel:[1,0]
	v_mov_b32_e32 v37, v20
	v_pk_add_f32 v[24:25], v[172:173], v[24:25] neg_lo:[0,1] neg_hi:[0,1]
	v_mov_b32_e32 v178, v174
	v_pk_add_f32 v[20:21], v[36:37], v[24:25] neg_lo:[0,1] neg_hi:[0,1]
	v_mov_b32_e32 v175, v23
	v_pk_add_f32 v[24:25], v[178:179], v[20:21]
	s_nop 0
	v_pk_add_f32 v[36:37], v[24:25], v[24:25] op_sel:[0,1] op_sel_hi:[1,0]
	s_nop 0
	v_pk_add_f32 v[22:23], v[22:23], v[36:37] op_sel:[1,0] op_sel_hi:[0,1]
	v_mov_b32_e32 v25, v22
	v_pk_add_f32 v[172:173], v[24:25], v[174:175] neg_lo:[0,1] neg_hi:[0,1]
	v_mov_b32_e32 v21, v36
	v_sub_f32_e32 v23, v24, v172
	v_pk_add_f32 v[20:21], v[20:21], v[172:173] neg_lo:[0,1] neg_hi:[0,1]
	v_sub_f32_e32 v23, v174, v23
	v_add_f32_e32 v20, v20, v23
	v_add_f32_e32 v20, v20, v21
	v_add_f32_e32 v20, v22, v20
	v_cndmask_b32_e32 v20, v171, v20, vcc
	v_cmp_lt_f32_e64 vcc, |v19|, s50
	s_nop 1
	v_cndmask_b32_e32 v19, v20, v19, vcc
.Lp0r_sp_done:
	s_or_b64 exec, exec, s[48:49]
	s_mov_b64 exec, s[4:5]
	global_store_dword v34, v19, s[52:53]
	s_mov_b64 exec, -1
	s_add_u32 s36, s36, s38
	s_cmp_lt_u32 s36, 0x10100
	s_cbranch_scc1 .Lp0r_loop
	s_waitcnt vmcnt(0)
	v_cmp_eq_u32_e64 s[6:7], 1, v176
